# NSA selected sweep: next-active tile search replaced by s_lshr+s_ff1 scalar sequence (was compiler-vectorized scalar loop)
# speedup vs baseline: 1.0156x; 1.0097x over previous
.LBB0_299:
	s_movk_i32 s0, 0x4800
	s_cmp_ge_i32 s42, s12
	v_mul_lo_u32 v0, v177, s0
	s_cselect_b64 s[38:39], -1, 0
	s_cmp_lt_i32 s42, s12
	v_add_u32_e32 v178, 0, v0
	s_cselect_b64 s[36:37], -1, 0
	s_mov_b32 s50, s12
	v_add3_u32 v0, v178, v156, v159
	s_and_b64 vcc, exec, s[36:37]
	s_mov_b32 s0, s51
	s_waitcnt vmcnt(3)
	ds_write_b128 v0, v[128:131]
	s_waitcnt vmcnt(2)
	ds_write_b128 v0, v[132:135] offset:9216
	s_waitcnt vmcnt(1)
	ds_write_b128 v0, v[136:139] offset:4608
	s_waitcnt vmcnt(0)
	ds_write_b128 v0, v[140:143] offset:13824
	s_waitcnt lgkmcnt(0)
	s_barrier
	s_cbranch_vccnz .LBB0_317
	s_add_i32 s12, s50, 1
	s_cmp_le_i32 s42, s50
	s_cbranch_scc1 .LBB0_316
	s_lshr_b32 s0, s33, s12
	s_ff1_i32_b32 s0, s0
	s_add_i32 s1, s42, 1
	s_cmp_lt_i32 s0, 0
	s_cselect_b32 s0, 32, s0
	s_add_i32 s12, s12, s0
	s_min_i32 s12, s12, s1
